# conflict-free LDS swizzle for 16x16x32 GEMM fragment reads (DMA source + read side remapped)
# speedup vs baseline: 1.0269x; 1.0054x over previous
.LBB0_115:
	s_cmpk_gt_i32 s88, 0x7f
	s_mov_b64 s[0:1], -1
	s_cbranch_scc0 .LBB0_130
	s_lshr_b32 s0, s88, 3
	s_add_i32 s24, s0, -16
	s_cmpk_gt_u32 s24, 0x11f
	s_cbranch_scc1 .LBB0_129
	v_readlane_b32 s0, v255, 16
	v_readlane_b32 s1, v255, 17
	s_mov_b32 s2, s0
	s_mul_i32 s1, s2, 0x840000
	v_readlane_b32 s4, v254, 62
	v_readlane_b32 s2, v253, 39
	v_readlane_b32 s12, v255, 6
	v_readlane_b32 s3, v253, 40
	s_add_u32 s42, s12, s1
	s_load_dword s1, s[2:3], 0x0
	s_mul_hi_i32 s0, s0, 0x840000
	v_readlane_b32 s13, v255, 7
	v_bfe_u32 v0, v160, 4, 2
	v_lshlrev_b32_e32 v2, 8, v160
	s_addc_u32 s43, s13, s0
	s_and_b32 s0, s88, 7
	v_lshrrev_b32_e32 v188, 1, v0
	v_xor_b32_e32 v0, v0, v188
	v_and_b32_e32 v0, 1, v0
	v_lshl_or_b32 v0, v0, 1, v188
	v_bitop3_b32 v0, v0, v160, 3 bitop3:0x78
	s_waitcnt vmcnt(2)
	v_lshrrev_b32_e32 v5, 2, v160
	v_bfe_u32 v8, v160, 5, 1
	v_and_b32_e32 v2, 0x3c00, v2
	v_ashrrev_i32_e32 v1, 6, v160
	s_xor_b32 s2, s0, 7
	v_bfe_u32 v6, v160, 2, 2
	s_lshl_b32 s45, s0, 4
	v_lshl_or_b32 v2, v0, 3, v2
	v_bitop3_b32 v0, v8, v5, 3 bitop3:0x78
	s_movk_i32 s0, 0x2400
	v_and_b32_e32 v7, 1, v1
	v_lshlrev_b32_e32 v157, 4, v0
	v_bitop3_b32 v0, v8, v6, 2 bitop3:0x36
	v_mul_lo_u32 v5, v1, s0
	v_and_b32_e32 v9, 7, v160
	v_lshlrev_b32_e32 v10, 2, v160
	s_waitcnt lgkmcnt(0)
	s_add_i32 s1, s1, s2
	v_and_b32_e32 v4, 31, v160
	v_lshlrev_b32_e32 v159, 4, v0
	v_lshl_or_b32 v6, v8, 3, v5
	v_lshlrev_b32_e32 v8, 6, v7
	v_lshlrev_b32_e32 v0, 3, v9
	v_bfe_u32 v172, v160, 3, 3
	v_and_b32_e32 v10, 4, v10
	s_movk_i32 s0, 0x1800
	v_lshlrev_b32_e32 v11, 6, v160
	v_lshlrev_b32_e32 v7, 12, v7
	s_lshr_b32 s44, s1, 3
	v_lshl_or_b32 v9, v9, 4, v5
	v_and_or_b32 v10, v0, 48, v10
	v_mul_lo_u32 v173, v1, s0
	v_and_b32_e32 v174, 0xffffe7c0, v11
	v_lshlrev_b32_e32 v11, 6, v4
	v_or_b32_e32 v12, v157, v7
	v_or_b32_e32 v7, v159, v7
	v_mul_u32_u24_e32 v4, 0x90, v4
	v_mul_u32_u24_e32 v13, 0x90, v172
	v_lshl_or_b32 v5, v172, 1, v5
	s_movk_i32 s0, 0x90
	s_add_i32 s76, s44, -16
	v_and_b32_e32 v161, 0xffffff80, v160
	v_or_b32_e32 v176, 8, v172
	v_or_b32_e32 v178, 16, v172
	v_or_b32_e32 v179, 24, v172
	v_or_b32_e32 v180, 32, v172
	v_or_b32_e32 v181, 40, v172
	v_or_b32_e32 v202, 48, v172
	v_or_b32_e32 v203, 56, v172
	v_mad_u32_u24 v204, v10, s0, v5
	v_or_b32_e32 v205, 0xfffffc00, v8
	v_or_b32_e32 v206, v8, v0
	v_lshlrev_b32_e32 v162, 1, v2
	v_mov_b32_e32 v163, v3
	v_lshlrev_b32_e32 v2, 1, v2
	v_add_u32_e32 v207, v12, v11
	v_add_u32_e32 v208, v7, v11
	v_add_u32_e32 v209, v6, v4
	v_add_u32_e32 v210, v9, v13
	v_readlane_b32 s5, v254, 63
	v_readlane_b32 s6, v255, 0
	v_readlane_b32 s7, v255, 1
	v_readlane_b32 s8, v255, 2
	v_readlane_b32 s9, v255, 3
	v_readlane_b32 s10, v255, 4
	v_readlane_b32 s11, v255, 5
	v_readlane_b32 s14, v255, 8
	v_readlane_b32 s15, v255, 9
	v_readlane_b32 s16, v255, 10
	v_readlane_b32 s17, v255, 11
	v_readlane_b32 s18, v255, 12
	v_readlane_b32 s19, v255, 13
	s_branch .LBB0_119

.LBB0_119:
	s_mul_hi_i32 s0, s24, 0x38e38e39
	s_lshr_b32 s1, s0, 31
	s_ashr_i32 s0, s0, 5
	s_add_i32 s0, s0, s1
	s_mul_i32 s1, s0, 0x90
	s_sub_i32 s1, s24, s1
	s_ashr_i32 s2, s1, 3
	s_add_i32 s3, s2, 15
	s_cmp_gt_i32 s2, 15
	s_cselect_b32 s47, s3, s2
	s_lshl_b32 s0, s0, 3
	s_add_i32 s0, s0, s45
	s_and_b32 s1, s1, 7
	s_or_b32 s0, s0, s1
	s_lshl_b32 s46, s47, 7
	s_lshl_b32 s48, s0, 8
	v_readfirstlane_b32 s49, v1
	s_add_i32 s57, s46, 0xffffff00
	s_cmp_lt_i32 s49, 3
	s_cselect_b64 s[0:1], -1, 0
	s_and_b64 s[2:3], s[0:1], exec
	s_mul_i32 s89, s49, 0x60
	s_cselect_b32 s2, s48, s57
	s_add_i32 s40, s2, s89
	s_and_b64 s[0:1], s[0:1], exec
	v_readlane_b32 s0, v254, 62
	v_readlane_b32 s1, v254, 63
	v_readlane_b32 s12, v255, 10
	v_readlane_b32 s13, v255, 11
	v_readlane_b32 s2, v255, 0
	v_readlane_b32 s3, v255, 1
	s_cselect_b32 s1, s13, s43
	s_cselect_b32 s0, s12, s42
	s_ashr_i32 s41, s40, 31
	s_lshl_b64 s[2:3], s[40:41], 11
	s_mul_i32 s20, s49, 6
	s_add_u32 s58, s0, s2
	s_addc_u32 s59, s1, s3
	s_or_b32 s38, s20, 1
	s_cmp_lt_i32 s38, 16
	s_cselect_b64 s[20:21], -1, 0
	s_lshl_b32 s41, s38, 4
	s_and_b64 s[38:39], s[20:21], exec
	s_cselect_b32 s44, s48, s57
	s_add_i32 s38, s44, s41
	s_and_b64 s[20:21], s[20:21], exec
	s_cselect_b32 s21, s13, s43
	s_cselect_b32 s20, s12, s42
	s_ashr_i32 s39, s38, 31
	s_lshl_b64 s[38:39], s[38:39], 11
	s_add_u32 s60, s20, s38
	s_addc_u32 s61, s21, s39
	s_add_i32 s38, s40, 32
	s_ashr_i32 s39, s38, 31
	s_lshl_b64 s[38:39], s[38:39], 11
	s_add_u32 s62, s0, s38
	s_addc_u32 s63, s1, s39
	s_add_i32 s40, s40, 48
	s_ashr_i32 s41, s40, 31
	s_lshl_b64 s[40:41], s[40:41], 11
	s_add_u32 s64, s0, s40
	s_addc_u32 s65, s1, s41
	s_cmp_lt_i32 s49, 2
	s_cselect_b64 s[40:41], -1, 0
	s_and_b64 s[66:67], s[40:41], exec
	s_cselect_b32 s49, s48, s57
	s_add_i32 s49, s89, s49
	s_add_i32 s66, s49, 64
	s_and_b64 s[40:41], s[40:41], exec
	s_cselect_b32 s41, s13, s43
	s_cselect_b32 s40, s12, s42
	s_ashr_i32 s67, s66, 31
	s_lshl_b64 s[66:67], s[66:67], 11
	s_add_u32 s68, s40, s66
	s_addc_u32 s69, s41, s67
	s_add_i32 vcc_lo, s49, 0x50
	s_ashr_i32 vcc_hi, vcc_lo, 31
	s_lshl_b64 vcc, vcc, 11
	s_add_u32 vcc_lo, s40, vcc_lo
	s_addc_u32 vcc_hi, s41, vcc_hi
	v_and_b32_e32 v188, 15, v160
	v_bfe_u32 v189, v160, 4, 2
	v_bfe_u32 v192, v188, 2, 2
	v_lshrrev_b32_e32 v193, 1, v192
	v_xor_b32_e32 v192, v192, v193
	v_and_b32_e32 v192, 1, v192
	v_lshl_or_b32 v192, v192, 1, v193
	v_xor_b32_e32 v189, v189, v192
	v_lshlrev_b32_e32 v189, 4, v189
	v_lshrrev_b32_e32 v192, 6, v160
	v_lshrrev_b32_e32 v193, 1, v192
	v_and_b32_e32 v192, 1, v192
	v_lshl_add_u32 v193, v193, 7, v188
	v_lshl_add_u32 v192, v192, 6, v188
	v_lshl_add_u32 v216, v193, 6, v189
	v_lshl_add_u32 v217, v192, 6, v189
	v_add_u32_e32 v217, 0x4000, v217
	v_add_u32_e32 v218, 0x6000, v216
	v_add_u32_e32 v219, 0x6000, v217
	v_readfirstlane_b32 s49, v173
	v_add_u32_e32 v220, 64, v2
	s_mov_b32 s3, s49
	s_mov_b32 m0, s3
	s_add_u32 s3, s3, 0x400
	global_load_lds_dwordx4 v2, s[58:59]
	s_mov_b32 m0, s3
	s_add_u32 s3, s3, 0x400
	global_load_lds_dwordx4 v2, s[60:61]
	s_mov_b32 m0, s3
	s_add_u32 s3, s3, 0x400
	global_load_lds_dwordx4 v2, s[62:63]
	s_mov_b32 m0, s3
	s_add_u32 s3, s3, 0x400
	global_load_lds_dwordx4 v2, s[64:65]
	s_mov_b32 m0, s3
	s_add_u32 s3, s3, 0x400
	global_load_lds_dwordx4 v2, s[68:69]
	s_mov_b32 m0, s3
	s_nop 0
	global_load_lds_dwordx4 v2, vcc
	s_waitcnt vmcnt(0)
	s_barrier
	s_add_u32 s3, s49, 0x6000
	s_mov_b32 m0, s3
	s_add_u32 s3, s3, 0x400
	global_load_lds_dwordx4 v220, s[58:59]
	s_mov_b32 m0, s3
	s_add_u32 s3, s3, 0x400
	global_load_lds_dwordx4 v220, s[60:61]
	s_mov_b32 m0, s3
	s_add_u32 s3, s3, 0x400
	global_load_lds_dwordx4 v220, s[62:63]
	s_mov_b32 m0, s3
	s_add_u32 s3, s3, 0x400
	global_load_lds_dwordx4 v220, s[64:65]
	s_mov_b32 m0, s3
	s_add_u32 s3, s3, 0x400
	global_load_lds_dwordx4 v220, s[68:69]
	s_mov_b32 m0, s3
	s_nop 0
	global_load_lds_dwordx4 v220, vcc
	v_add_u32_e32 v220, 0x80, v2
	ds_read_b128 v[132:135], v217
	ds_read_b128 v[136:139], v217 offset:1024
	ds_read_b128 v[140:143], v217 offset:2048
	ds_read_b128 v[144:147], v217 offset:3072
	ds_read_b128 v[240:243], v216
	ds_read_b128 v[244:247], v216 offset:1024
	ds_read_b128 v[248:251], v216 offset:2048
	ds_read_b128 v[148:151], v216 offset:3072
	v_mov_b32_e32 v4, 0
	v_mov_b32_e32 v5, v4
	v_mov_b32_e32 v6, v4
	v_mov_b32_e32 v7, v4
	v_mov_b32_e32 v8, v4
	v_mov_b32_e32 v9, v4
	v_mov_b32_e32 v10, v4
	v_mov_b32_e32 v11, v4
	v_mov_b32_e32 v12, v4
	v_mov_b32_e32 v13, v4
	v_mov_b32_e32 v14, v4
	v_mov_b32_e32 v15, v4
	v_mov_b32_e32 v16, v4
	v_mov_b32_e32 v17, v4
	v_mov_b32_e32 v18, v4
	v_mov_b32_e32 v19, v4
	v_mov_b32_e32 v20, v4
	v_mov_b32_e32 v21, v4
	v_mov_b32_e32 v22, v4
	v_mov_b32_e32 v23, v4
	v_mov_b32_e32 v24, v4
	v_mov_b32_e32 v25, v4
	v_mov_b32_e32 v26, v4
	v_mov_b32_e32 v27, v4
	v_mov_b32_e32 v28, v4
	v_mov_b32_e32 v29, v4
	v_mov_b32_e32 v30, v4
	v_mov_b32_e32 v31, v4
	v_mov_b32_e32 v32, v4
	v_mov_b32_e32 v33, v4
	v_mov_b32_e32 v34, v4
	v_mov_b32_e32 v35, v4
	v_mov_b32_e32 v36, v4
	v_mov_b32_e32 v37, v4
	v_mov_b32_e32 v38, v4
	v_mov_b32_e32 v39, v4
	v_mov_b32_e32 v40, v4
	v_mov_b32_e32 v41, v4
	v_mov_b32_e32 v42, v4
	v_mov_b32_e32 v43, v4
	v_mov_b32_e32 v44, v4
	v_mov_b32_e32 v45, v4
	v_mov_b32_e32 v46, v4
	v_mov_b32_e32 v47, v4
	v_mov_b32_e32 v48, v4
	v_mov_b32_e32 v49, v4
	v_mov_b32_e32 v50, v4
	v_mov_b32_e32 v51, v4
	v_mov_b32_e32 v52, v4
	v_mov_b32_e32 v53, v4
	v_mov_b32_e32 v54, v4
	v_mov_b32_e32 v55, v4
	v_mov_b32_e32 v56, v4
	v_mov_b32_e32 v57, v4
	v_mov_b32_e32 v58, v4
	v_mov_b32_e32 v59, v4
	v_mov_b32_e32 v60, v4
	v_mov_b32_e32 v61, v4
	v_mov_b32_e32 v62, v4
	v_mov_b32_e32 v63, v4
	v_mov_b32_e32 v64, v4
	v_mov_b32_e32 v65, v4
	v_mov_b32_e32 v66, v4
	v_mov_b32_e32 v67, v4
	v_mov_b32_e32 v68, v4
	v_mov_b32_e32 v69, v4
	v_mov_b32_e32 v70, v4
	v_mov_b32_e32 v71, v4
	v_mov_b32_e32 v72, v4
	v_mov_b32_e32 v73, v4
	v_mov_b32_e32 v74, v4
	v_mov_b32_e32 v75, v4
	v_mov_b32_e32 v76, v4
	v_mov_b32_e32 v77, v4
	v_mov_b32_e32 v78, v4
	v_mov_b32_e32 v79, v4
	v_mov_b32_e32 v80, v4
	v_mov_b32_e32 v81, v4
	v_mov_b32_e32 v82, v4
	v_mov_b32_e32 v83, v4
	v_mov_b32_e32 v84, v4
	v_mov_b32_e32 v85, v4
	v_mov_b32_e32 v86, v4
	v_mov_b32_e32 v87, v4
	v_mov_b32_e32 v88, v4
	v_mov_b32_e32 v89, v4
	v_mov_b32_e32 v90, v4
	v_mov_b32_e32 v91, v4
	v_mov_b32_e32 v92, v4
	v_mov_b32_e32 v93, v4
	v_mov_b32_e32 v94, v4
	v_mov_b32_e32 v95, v4
	v_mov_b32_e32 v96, v4
	v_mov_b32_e32 v97, v4
	v_mov_b32_e32 v98, v4
	v_mov_b32_e32 v99, v4
	v_mov_b32_e32 v100, v4
	v_mov_b32_e32 v101, v4
	v_mov_b32_e32 v102, v4
	v_mov_b32_e32 v103, v4
	v_mov_b32_e32 v104, v4
	v_mov_b32_e32 v105, v4
	v_mov_b32_e32 v106, v4
	v_mov_b32_e32 v107, v4
	v_mov_b32_e32 v108, v4
	v_mov_b32_e32 v109, v4
	v_mov_b32_e32 v110, v4
	v_mov_b32_e32 v111, v4
	v_mov_b32_e32 v112, v4
	v_mov_b32_e32 v113, v4
	v_mov_b32_e32 v114, v4
	v_mov_b32_e32 v115, v4
	v_mov_b32_e32 v116, v4
	v_mov_b32_e32 v117, v4
	v_mov_b32_e32 v118, v4
	v_mov_b32_e32 v119, v4
	v_mov_b32_e32 v120, v4
	v_mov_b32_e32 v121, v4
	v_mov_b32_e32 v122, v4
	v_mov_b32_e32 v123, v4
	v_mov_b32_e32 v124, v4
	v_mov_b32_e32 v125, v4
	v_mov_b32_e32 v126, v4
	v_mov_b32_e32 v127, v4
	v_mov_b32_e32 v128, v4
	v_mov_b32_e32 v129, v4
	v_mov_b32_e32 v130, v4
	v_mov_b32_e32 v131, v4
	s_mov_b32 s0, 0

.LBB0_236:
	s_andn2_b64 vcc, exec, s[0:1]
	s_cbranch_vccnz .LBB0_251
	s_ashr_i32 s24, s88, 3
	s_cmpk_gt_i32 s24, 0xef
	s_cbranch_scc1 .LBB0_251
	v_readlane_b32 s0, v255, 16
	v_readlane_b32 s1, v255, 17
	s_mov_b32 s2, s0
	s_mul_i32 s1, s2, 0x840000
	v_readlane_b32 s4, v254, 62
	v_readlane_b32 s2, v253, 39
	v_readlane_b32 s12, v255, 6
	v_readlane_b32 s3, v253, 40
	s_mul_hi_i32 s0, s0, 0x840000
	v_readlane_b32 s13, v255, 7
	s_add_u32 s42, s12, s1
	s_load_dword s1, s[2:3], 0x0
	v_bfe_u32 v0, v160, 4, 2
	v_lshlrev_b32_e32 v2, 8, v160
	s_addc_u32 s43, s13, s0
	s_and_b32 s0, s88, 7
	v_lshrrev_b32_e32 v188, 1, v0
	v_xor_b32_e32 v0, v0, v188
	v_and_b32_e32 v0, 1, v0
	v_lshl_or_b32 v0, v0, 1, v188
	v_bitop3_b32 v0, v0, v160, 3 bitop3:0x78
	s_waitcnt vmcnt(2)
	v_lshrrev_b32_e32 v5, 2, v160
	v_bfe_u32 v8, v160, 5, 1
	v_and_b32_e32 v2, 0x3c00, v2
	v_ashrrev_i32_e32 v1, 6, v160
	s_xor_b32 s2, s0, 7
	v_bfe_u32 v6, v160, 2, 2
	s_lshl_b32 s45, s0, 4
	v_lshl_or_b32 v2, v0, 3, v2
	v_bitop3_b32 v0, v8, v5, 3 bitop3:0x78
	s_movk_i32 s0, 0x2400
	v_and_b32_e32 v7, 1, v1
	v_lshlrev_b32_e32 v157, 4, v0
	v_bitop3_b32 v0, v8, v6, 2 bitop3:0x36
	v_mul_lo_u32 v5, v1, s0
	v_and_b32_e32 v9, 7, v160
	v_lshlrev_b32_e32 v10, 2, v160
	v_and_b32_e32 v4, 31, v160
	v_lshlrev_b32_e32 v159, 4, v0
	v_lshl_or_b32 v6, v8, 3, v5
	v_lshlrev_b32_e32 v8, 6, v7
	v_lshlrev_b32_e32 v0, 3, v9
	v_bfe_u32 v172, v160, 3, 3
	v_and_b32_e32 v10, 4, v10
	s_movk_i32 s0, 0x1800
	v_lshlrev_b32_e32 v11, 6, v160
	v_lshlrev_b32_e32 v7, 12, v7
	s_waitcnt lgkmcnt(0)
	s_add_i32 s1, s1, s2
	v_lshl_or_b32 v9, v9, 4, v5
	v_and_or_b32 v10, v0, 48, v10
	v_mul_lo_u32 v173, v1, s0
	v_and_b32_e32 v174, 0xffffe7c0, v11
	v_lshlrev_b32_e32 v11, 6, v4
	v_or_b32_e32 v12, v157, v7
	v_or_b32_e32 v7, v159, v7
	v_mul_u32_u24_e32 v4, 0x90, v4
	v_mul_u32_u24_e32 v13, 0x90, v172
	v_lshl_or_b32 v5, v172, 1, v5
	s_movk_i32 s0, 0x90
	s_lshr_b32 s76, s1, 3
	v_and_b32_e32 v161, 0xffffff80, v160
	v_or_b32_e32 v176, 8, v172
	v_or_b32_e32 v178, 16, v172
	v_or_b32_e32 v179, 24, v172
	v_or_b32_e32 v180, 32, v172
	v_or_b32_e32 v181, 40, v172
	v_or_b32_e32 v202, 48, v172
	v_or_b32_e32 v203, 56, v172
	v_mad_u32_u24 v204, v10, s0, v5
	v_or_b32_e32 v205, 0xfffffc00, v8
	v_or_b32_e32 v206, v8, v0
	v_lshlrev_b32_e32 v162, 1, v2
	v_mov_b32_e32 v163, v3
	v_lshlrev_b32_e32 v2, 1, v2
	v_add_u32_e32 v207, v12, v11
	v_add_u32_e32 v208, v7, v11
	v_add_u32_e32 v209, v6, v4
	v_add_u32_e32 v210, v9, v13
	v_readlane_b32 s5, v254, 63
	v_readlane_b32 s6, v255, 0
	v_readlane_b32 s7, v255, 1
	v_readlane_b32 s8, v255, 2
	v_readlane_b32 s9, v255, 3
	v_readlane_b32 s10, v255, 4
	v_readlane_b32 s11, v255, 5
	v_readlane_b32 s14, v255, 8
	v_readlane_b32 s15, v255, 9
	v_readlane_b32 s16, v255, 10
	v_readlane_b32 s17, v255, 11
	v_readlane_b32 s18, v255, 12
	v_readlane_b32 s19, v255, 13
	s_branch .LBB0_240

.LBB0_240:
	s_mul_hi_i32 s0, s24, 0x88888889
	s_add_i32 s0, s0, s24
	s_lshr_b32 s1, s0, 31
	s_ashr_i32 s0, s0, 6
	s_add_i32 s0, s0, s1
	s_mul_i32 s1, s0, 0x78
	s_sub_i32 s1, s24, s1
	s_ashr_i32 s47, s1, 3
	s_lshl_b32 s0, s0, 3
	s_add_i32 s48, s47, 16
	s_add_i32 s0, s0, s45
	s_and_b32 s1, s1, 7
	s_or_b32 s0, s0, s1
	s_lshl_b32 s46, s48, 7
	s_lshl_b32 s49, s0, 8
	v_readfirstlane_b32 s66, v1
	s_add_i32 s68, s46, 0xffffff00
	s_cmp_lt_i32 s66, 3
	s_cselect_b64 s[0:1], -1, 0
	s_and_b64 s[2:3], s[0:1], exec
	s_mul_i32 s89, s66, 0x60
	s_cselect_b32 s2, s49, s68
	s_add_i32 s40, s2, s89
	s_and_b64 s[0:1], s[0:1], exec
	v_readlane_b32 s0, v254, 62
	v_readlane_b32 s1, v254, 63
	v_readlane_b32 s12, v255, 10
	v_readlane_b32 s13, v255, 11
	v_readlane_b32 s2, v255, 0
	v_readlane_b32 s3, v255, 1
	s_cselect_b32 s1, s13, s43
	s_cselect_b32 s0, s12, s42
	s_ashr_i32 s41, s40, 31
	s_lshl_b64 s[2:3], s[40:41], 11
	s_mul_i32 s20, s66, 6
	s_add_u32 s58, s0, s2
	s_addc_u32 s59, s1, s3
	s_or_b32 s38, s20, 1
	s_cmp_lt_i32 s38, 16
	s_cselect_b64 s[20:21], -1, 0
	s_lshl_b32 s41, s38, 4
	s_and_b64 s[38:39], s[20:21], exec
	s_cselect_b32 s57, s49, s68
	s_add_i32 s38, s57, s41
	s_and_b64 s[20:21], s[20:21], exec
	s_cselect_b32 s21, s13, s43
	s_cselect_b32 s20, s12, s42
	s_ashr_i32 s39, s38, 31
	s_lshl_b64 s[38:39], s[38:39], 11
	s_add_u32 s60, s20, s38
	s_addc_u32 s61, s21, s39
	s_add_i32 s38, s40, 32
	s_ashr_i32 s39, s38, 31
	s_lshl_b64 s[38:39], s[38:39], 11
	s_add_u32 s62, s0, s38
	s_addc_u32 s63, s1, s39
	s_add_i32 s40, s40, 48
	s_ashr_i32 s41, s40, 31
	s_lshl_b64 s[40:41], s[40:41], 11
	s_add_u32 s64, s0, s40
	s_addc_u32 s65, s1, s41
	s_cmp_lt_i32 s66, 2
	s_cselect_b64 s[40:41], -1, 0
	s_and_b64 s[66:67], s[40:41], exec
	s_cselect_b32 s66, s49, s68
	s_add_i32 vcc_lo, s89, s66
	s_add_i32 s66, vcc_lo, 64
	s_and_b64 s[40:41], s[40:41], exec
	s_cselect_b32 s41, s13, s43
	s_cselect_b32 s40, s12, s42
	s_ashr_i32 s67, s66, 31
	s_lshl_b64 s[66:67], s[66:67], 11
	s_add_u32 s68, s40, s66
	s_addc_u32 s69, s41, s67
	s_addk_i32 vcc_lo, 0x50
	s_ashr_i32 vcc_hi, vcc_lo, 31
	s_lshl_b64 vcc, vcc, 11
	s_add_u32 vcc_lo, s40, vcc_lo
	s_addc_u32 vcc_hi, s41, vcc_hi
	v_and_b32_e32 v188, 15, v160
	v_bfe_u32 v189, v160, 4, 2
	v_bfe_u32 v192, v188, 2, 2
	v_lshrrev_b32_e32 v193, 1, v192
	v_xor_b32_e32 v192, v192, v193
	v_and_b32_e32 v192, 1, v192
	v_lshl_or_b32 v192, v192, 1, v193
	v_xor_b32_e32 v189, v189, v192
	v_lshlrev_b32_e32 v189, 4, v189
	v_lshrrev_b32_e32 v192, 6, v160
	v_lshrrev_b32_e32 v193, 1, v192
	v_and_b32_e32 v192, 1, v192
	v_lshl_add_u32 v193, v193, 7, v188
	v_lshl_add_u32 v192, v192, 6, v188
	v_lshl_add_u32 v216, v193, 6, v189
	v_lshl_add_u32 v217, v192, 6, v189
	v_add_u32_e32 v217, 0x4000, v217
	v_add_u32_e32 v218, 0x6000, v216
	v_add_u32_e32 v219, 0x6000, v217
	v_readfirstlane_b32 s44, v173
	v_add_u32_e32 v220, 64, v2
	s_mov_b32 s3, s44
	s_mov_b32 m0, s3
	s_add_u32 s3, s3, 0x400
	global_load_lds_dwordx4 v2, s[58:59]
	s_mov_b32 m0, s3
	s_add_u32 s3, s3, 0x400
	global_load_lds_dwordx4 v2, s[60:61]
	s_mov_b32 m0, s3
	s_add_u32 s3, s3, 0x400
	global_load_lds_dwordx4 v2, s[62:63]
	s_mov_b32 m0, s3
	s_add_u32 s3, s3, 0x400
	global_load_lds_dwordx4 v2, s[64:65]
	s_mov_b32 m0, s3
	s_add_u32 s3, s3, 0x400
	global_load_lds_dwordx4 v2, s[68:69]
	s_mov_b32 m0, s3
	s_nop 0
	global_load_lds_dwordx4 v2, vcc
	s_waitcnt vmcnt(0)
	s_barrier
	s_add_u32 s3, s44, 0x6000
	s_mov_b32 m0, s3
	s_add_u32 s3, s3, 0x400
	global_load_lds_dwordx4 v220, s[58:59]
	s_mov_b32 m0, s3
	s_add_u32 s3, s3, 0x400
	global_load_lds_dwordx4 v220, s[60:61]
	s_mov_b32 m0, s3
	s_add_u32 s3, s3, 0x400
	global_load_lds_dwordx4 v220, s[62:63]
	s_mov_b32 m0, s3
	s_add_u32 s3, s3, 0x400
	global_load_lds_dwordx4 v220, s[64:65]
	s_mov_b32 m0, s3
	s_add_u32 s3, s3, 0x400
	global_load_lds_dwordx4 v220, s[68:69]
	s_mov_b32 m0, s3
	s_nop 0
	global_load_lds_dwordx4 v220, vcc
	v_add_u32_e32 v220, 0x80, v2
	ds_read_b128 v[132:135], v217
	ds_read_b128 v[136:139], v217 offset:1024
	ds_read_b128 v[140:143], v217 offset:2048
	ds_read_b128 v[144:147], v217 offset:3072
	ds_read_b128 v[240:243], v216
	ds_read_b128 v[244:247], v216 offset:1024
	ds_read_b128 v[248:251], v216 offset:2048
	ds_read_b128 v[148:151], v216 offset:3072
	v_mov_b32_e32 v4, 0
	v_mov_b32_e32 v5, v4
	v_mov_b32_e32 v6, v4
	v_mov_b32_e32 v7, v4
	v_mov_b32_e32 v8, v4
	v_mov_b32_e32 v9, v4
	v_mov_b32_e32 v10, v4
	v_mov_b32_e32 v11, v4
	v_mov_b32_e32 v12, v4
	v_mov_b32_e32 v13, v4
	v_mov_b32_e32 v14, v4
	v_mov_b32_e32 v15, v4
	v_mov_b32_e32 v16, v4
	v_mov_b32_e32 v17, v4
	v_mov_b32_e32 v18, v4
	v_mov_b32_e32 v19, v4
	v_mov_b32_e32 v20, v4
	v_mov_b32_e32 v21, v4
	v_mov_b32_e32 v22, v4
	v_mov_b32_e32 v23, v4
	v_mov_b32_e32 v24, v4
	v_mov_b32_e32 v25, v4
	v_mov_b32_e32 v26, v4
	v_mov_b32_e32 v27, v4
	v_mov_b32_e32 v28, v4
	v_mov_b32_e32 v29, v4
	v_mov_b32_e32 v30, v4
	v_mov_b32_e32 v31, v4
	v_mov_b32_e32 v32, v4
	v_mov_b32_e32 v33, v4
	v_mov_b32_e32 v34, v4
	v_mov_b32_e32 v35, v4
	v_mov_b32_e32 v36, v4
	v_mov_b32_e32 v37, v4
	v_mov_b32_e32 v38, v4
	v_mov_b32_e32 v39, v4
	v_mov_b32_e32 v40, v4
	v_mov_b32_e32 v41, v4
	v_mov_b32_e32 v42, v4
	v_mov_b32_e32 v43, v4
	v_mov_b32_e32 v44, v4
	v_mov_b32_e32 v45, v4
	v_mov_b32_e32 v46, v4
	v_mov_b32_e32 v47, v4
	v_mov_b32_e32 v48, v4
	v_mov_b32_e32 v49, v4
	v_mov_b32_e32 v50, v4
	v_mov_b32_e32 v51, v4
	v_mov_b32_e32 v52, v4
	v_mov_b32_e32 v53, v4
	v_mov_b32_e32 v54, v4
	v_mov_b32_e32 v55, v4
	v_mov_b32_e32 v56, v4
	v_mov_b32_e32 v57, v4
	v_mov_b32_e32 v58, v4
	v_mov_b32_e32 v59, v4
	v_mov_b32_e32 v60, v4
	v_mov_b32_e32 v61, v4
	v_mov_b32_e32 v62, v4
	v_mov_b32_e32 v63, v4
	v_mov_b32_e32 v64, v4
	v_mov_b32_e32 v65, v4
	v_mov_b32_e32 v66, v4
	v_mov_b32_e32 v67, v4
	v_mov_b32_e32 v68, v4
	v_mov_b32_e32 v69, v4
	v_mov_b32_e32 v70, v4
	v_mov_b32_e32 v71, v4
	v_mov_b32_e32 v72, v4
	v_mov_b32_e32 v73, v4
	v_mov_b32_e32 v74, v4
	v_mov_b32_e32 v75, v4
	v_mov_b32_e32 v76, v4
	v_mov_b32_e32 v77, v4
	v_mov_b32_e32 v78, v4
	v_mov_b32_e32 v79, v4
	v_mov_b32_e32 v80, v4
	v_mov_b32_e32 v81, v4
	v_mov_b32_e32 v82, v4
	v_mov_b32_e32 v83, v4
	v_mov_b32_e32 v84, v4
	v_mov_b32_e32 v85, v4
	v_mov_b32_e32 v86, v4
	v_mov_b32_e32 v87, v4
	v_mov_b32_e32 v88, v4
	v_mov_b32_e32 v89, v4
	v_mov_b32_e32 v90, v4
	v_mov_b32_e32 v91, v4
	v_mov_b32_e32 v92, v4
	v_mov_b32_e32 v93, v4
	v_mov_b32_e32 v94, v4
	v_mov_b32_e32 v95, v4
	v_mov_b32_e32 v96, v4
	v_mov_b32_e32 v97, v4
	v_mov_b32_e32 v98, v4
	v_mov_b32_e32 v99, v4
	v_mov_b32_e32 v100, v4
	v_mov_b32_e32 v101, v4
	v_mov_b32_e32 v102, v4
	v_mov_b32_e32 v103, v4
	v_mov_b32_e32 v104, v4
	v_mov_b32_e32 v105, v4
	v_mov_b32_e32 v106, v4
	v_mov_b32_e32 v107, v4
	v_mov_b32_e32 v108, v4
	v_mov_b32_e32 v109, v4
	v_mov_b32_e32 v110, v4
	v_mov_b32_e32 v111, v4
	v_mov_b32_e32 v112, v4
	v_mov_b32_e32 v113, v4
	v_mov_b32_e32 v114, v4
	v_mov_b32_e32 v115, v4
	v_mov_b32_e32 v116, v4
	v_mov_b32_e32 v117, v4
	v_mov_b32_e32 v118, v4
	v_mov_b32_e32 v119, v4
	v_mov_b32_e32 v120, v4
	v_mov_b32_e32 v121, v4
	v_mov_b32_e32 v122, v4
	v_mov_b32_e32 v123, v4
	v_mov_b32_e32 v124, v4
	v_mov_b32_e32 v125, v4
	v_mov_b32_e32 v126, v4
	v_mov_b32_e32 v127, v4
	v_mov_b32_e32 v128, v4
	v_mov_b32_e32 v129, v4
	v_mov_b32_e32 v130, v4
	v_mov_b32_e32 v131, v4
	s_mov_b32 s0, 0

.LBB0_254:
	s_nop 0
	v_readlane_b32 s0, v255, 19
	v_readlane_b32 s1, v255, 20
	s_and_b64 vcc, exec, s[0:1]
	s_cbranch_vccz .LBB0_261
	s_ashr_i32 s24, s88, 3
	s_cmpk_gt_i32 s24, 0x7f
	s_cbranch_scc1 .LBB0_260
	v_readlane_b32 s0, v255, 16
	v_readlane_b32 s1, v255, 17
	s_mov_b32 s2, s0
	s_ashr_i32 s3, s0, 31
	v_writelane_b32 v255, s0, 16
	v_readlane_b32 s4, v254, 62
	s_waitcnt vmcnt(2)
	v_bfe_u32 v4, v160, 4, 2
	v_writelane_b32 v255, s1, 17
	s_lshl_b64 s[0:1], s[2:3], 21
	v_readlane_b32 s2, v253, 39
	v_readlane_b32 s14, v255, 8
	v_readlane_b32 s3, v253, 40
	s_add_u32 s46, s14, s0
	s_load_dword s0, s[2:3], 0x0
	v_readlane_b32 s15, v255, 9
	s_addc_u32 s47, s15, s1
	s_and_b32 s1, s88, 7
	s_xor_b32 s2, s1, 7
	v_lshlrev_b32_e32 v2, 8, v160
	s_waitcnt lgkmcnt(0)
	s_add_i32 s0, s0, s2
	v_lshrrev_b32_e32 v188, 1, v4
	v_xor_b32_e32 v189, v4, v188
	v_and_b32_e32 v189, 1, v189
	v_lshl_or_b32 v189, v189, 1, v188
	v_bitop3_b32 v0, v189, v160, 3 bitop3:0x78
	v_lshrrev_b32_e32 v5, 2, v160
	v_bfe_u32 v8, v160, 5, 1
	v_and_b32_e32 v2, 0x3c00, v2
	s_lshr_b32 s48, s0, 3
	v_bfe_u32 v6, v160, 2, 2
	s_lshl_b32 s49, s1, 4
	v_lshl_or_b32 v2, v0, 3, v2
	v_bitop3_b32 v0, v8, v5, 3 bitop3:0x78
	v_readlane_b32 s0, v253, 3
	v_lshlrev_b32_e32 v157, 4, v0
	v_bitop3_b32 v0, v8, v6, 2 bitop3:0x36
	s_add_i32 s0, s0, 5
	v_ashrrev_i32_e32 v1, 6, v160
	v_lshlrev_b32_e32 v159, 4, v0
	s_cmp_lt_u32 s0, 13
	s_movk_i32 s0, 0x2200
	v_lshlrev_b32_e32 v0, 2, v160
	v_and_b32_e32 v7, 1, v1
	v_and_b32_e32 v9, 31, v160
	v_mul_lo_u32 v5, v1, s0
	v_and_b32_e32 v6, 60, v0
	s_movk_i32 s0, 0x110
	v_lshl_or_b32 v0, v7, 6, v6
	v_mad_u32_u24 v10, v9, s0, v5
	v_lshl_or_b32 v5, v6, 2, v5
	v_lshlrev_b32_e32 v6, 6, v160
	v_and_b32_e32 v173, 0xffffe7c0, v6
	v_lshlrev_b32_e32 v6, 12, v7
	v_readlane_b32 s60, v253, 7
	v_readlane_b32 s10, v255, 4
	v_readlane_b32 s11, v255, 5
	v_readlane_b32 s1, v253, 4
	v_and_or_b32 v161, v160, s52, v4
	v_lshlrev_b32_e32 v8, 4, v8
	s_movk_i32 s0, 0x1800
	v_lshlrev_b32_e32 v7, 6, v9
	v_or_b32_e32 v9, v157, v6
	v_or_b32_e32 v6, v159, v6
	v_mul_u32_u24_e32 v4, 0x110, v4
	v_readlane_b32 s61, v253, 8
	v_mul_lo_u32 v172, v1, s0
	s_cselect_b32 s1, s61, s11
	s_cselect_b32 s0, s60, s10
	v_lshlrev_b32_e32 v162, 1, v2
	v_mov_b32_e32 v163, v3
	v_lshlrev_b32_e32 v2, 1, v2
	v_add_u32_e32 v174, v10, v8
	v_add_u32_e32 v176, v5, v4
	v_add_u32_e32 v178, v9, v7
	v_add_u32_e32 v179, v6, v7
	v_readlane_b32 s5, v254, 63
	v_readlane_b32 s6, v255, 0
	v_readlane_b32 s7, v255, 1
	v_readlane_b32 s8, v255, 2
	v_readlane_b32 s9, v255, 3
	v_readlane_b32 s12, v255, 6
	v_readlane_b32 s13, v255, 7
	v_readlane_b32 s16, v255, 10
	v_readlane_b32 s17, v255, 11
	v_readlane_b32 s18, v255, 12
	v_readlane_b32 s19, v255, 13
	v_readlane_b32 s2, v253, 5
	v_readlane_b32 s3, v253, 6
	v_readlane_b32 s62, v253, 9
	v_readlane_b32 s63, v253, 10
	v_readlane_b32 s64, v253, 11
	v_readlane_b32 s65, v253, 12
	v_readlane_b32 s66, v253, 13
	v_readlane_b32 s67, v253, 14
	v_readlane_b32 s68, v253, 15
	v_readlane_b32 s69, v253, 16
	v_readlane_b32 s70, v253, 17
	v_readlane_b32 s71, v253, 18
	v_readlane_b32 s72, v253, 19
	v_readlane_b32 s73, v253, 20
	v_readlane_b32 s74, v253, 21
	v_readlane_b32 s75, v253, 22
.LBB0_257:
	s_ashr_i32 s2, s24, 31
	s_lshr_b32 s2, s2, 26
	s_add_i32 s2, s24, s2
	s_and_b32 s3, s2, 0xffffffc0
	s_lshr_b32 s2, s2, 3
	s_sub_i32 s3, s24, s3
	s_and_b32 s2, s2, 0x1ffffff8
	s_add_i32 s2, s2, s49
	s_and_b32 s20, s3, 7
	s_or_b32 s2, s2, s20
	s_lshl_b32 s39, s2, 8
	s_lshl_b32 s2, s3, 4
	s_and_b32 s38, s2, 0xffffff80
	v_readfirstlane_b32 s57, v1
	s_add_i32 s68, s38, 0xffffff00
	s_cmp_lt_i32 s57, 3
	s_cselect_b64 s[2:3], -1, 0
	s_and_b64 s[20:21], s[2:3], exec
	s_mul_i32 s89, s57, 0x60
	s_cselect_b32 s20, s39, s68
	s_add_i32 s44, s20, s89
	v_readlane_b32 s72, v254, 44
	s_and_b64 s[2:3], s[2:3], exec
	v_readlane_b32 s74, v254, 46
	v_readlane_b32 s75, v254, 47
	s_cselect_b32 s3, s75, s47
	s_cselect_b32 s2, s74, s46
	s_ashr_i32 s45, s44, 31
	s_lshl_b64 s[20:21], s[44:45], 11
	s_mul_i32 s40, s57, 6
	s_add_u32 s58, s2, s20
	s_addc_u32 s59, s3, s21
	s_or_b32 s42, s40, 1
	s_cmp_lt_i32 s42, 16
	s_cselect_b64 s[40:41], -1, 0
	s_lshl_b32 s45, s42, 4
	s_and_b64 s[42:43], s[40:41], exec
	s_cselect_b32 s30, s39, s68
	s_add_i32 s42, s30, s45
	s_and_b64 s[40:41], s[40:41], exec
	s_cselect_b32 s41, s75, s47
	s_cselect_b32 s40, s74, s46
	s_ashr_i32 s43, s42, 31
	s_lshl_b64 s[42:43], s[42:43], 11
	s_add_u32 s60, s40, s42
	s_addc_u32 s61, s41, s43
	s_add_i32 s42, s44, 32
	s_ashr_i32 s43, s42, 31
	s_lshl_b64 s[42:43], s[42:43], 11
	s_add_u32 s62, s2, s42
	s_addc_u32 s63, s3, s43
	s_add_i32 s44, s44, 48
	s_ashr_i32 s45, s44, 31
	s_lshl_b64 s[44:45], s[44:45], 11
	s_add_u32 s64, s2, s44
	s_addc_u32 s65, s3, s45
	s_cmp_lt_i32 s57, 2
	s_cselect_b64 s[44:45], -1, 0
	s_and_b64 s[66:67], s[44:45], exec
	s_cselect_b32 s31, s39, s68
	s_add_i32 s31, s89, s31
	s_add_i32 s66, s31, 64
	s_and_b64 s[44:45], s[44:45], exec
	s_cselect_b32 s45, s75, s47
	s_cselect_b32 s44, s74, s46
	s_ashr_i32 s67, s66, 31
	s_lshl_b64 s[66:67], s[66:67], 11
	s_add_u32 s68, s44, s66
	s_addc_u32 s69, s45, s67
	s_add_i32 vcc_lo, s31, 0x50
	s_ashr_i32 vcc_hi, vcc_lo, 31
	s_lshl_b64 vcc, vcc, 11
	s_add_u32 vcc_lo, s44, vcc_lo
	s_addc_u32 vcc_hi, s45, vcc_hi
	v_and_b32_e32 v188, 15, v160
	v_bfe_u32 v189, v160, 4, 2
	v_bfe_u32 v192, v188, 2, 2
	v_lshrrev_b32_e32 v193, 1, v192
	v_xor_b32_e32 v192, v192, v193
	v_and_b32_e32 v192, 1, v192
	v_lshl_or_b32 v192, v192, 1, v193
	v_xor_b32_e32 v189, v189, v192
	v_lshlrev_b32_e32 v189, 4, v189
	v_lshrrev_b32_e32 v192, 6, v160
	v_lshrrev_b32_e32 v193, 1, v192
	v_and_b32_e32 v192, 1, v192
	v_lshl_add_u32 v193, v193, 7, v188
	v_lshl_add_u32 v192, v192, 6, v188
	v_lshl_add_u32 v216, v193, 6, v189
	v_lshl_add_u32 v217, v192, 6, v189
	v_add_u32_e32 v217, 0x4000, v217
	v_add_u32_e32 v218, 0x6000, v216
	v_add_u32_e32 v219, 0x6000, v217
	v_readfirstlane_b32 s31, v172
	v_add_u32_e32 v220, 64, v2
	s_mov_b32 s41, s31
	s_mov_b32 m0, s41
	s_add_u32 s41, s41, 0x400
	global_load_lds_dwordx4 v2, s[58:59]
	s_mov_b32 m0, s41
	s_add_u32 s41, s41, 0x400
	global_load_lds_dwordx4 v2, s[60:61]
	s_mov_b32 m0, s41
	s_add_u32 s41, s41, 0x400
	global_load_lds_dwordx4 v2, s[62:63]
	s_mov_b32 m0, s41
	s_add_u32 s41, s41, 0x400
	global_load_lds_dwordx4 v2, s[64:65]
	s_mov_b32 m0, s41
	s_add_u32 s41, s41, 0x400
	global_load_lds_dwordx4 v2, s[68:69]
	s_mov_b32 m0, s41
	s_nop 0
	global_load_lds_dwordx4 v2, vcc
	s_waitcnt vmcnt(0)
	s_barrier
	s_add_u32 s41, s31, 0x6000
	s_mov_b32 m0, s41
	s_add_u32 s41, s41, 0x400
	global_load_lds_dwordx4 v220, s[58:59]
	s_mov_b32 m0, s41
	s_add_u32 s41, s41, 0x400
	global_load_lds_dwordx4 v220, s[60:61]
	s_mov_b32 m0, s41
	s_add_u32 s41, s41, 0x400
	global_load_lds_dwordx4 v220, s[62:63]
	s_mov_b32 m0, s41
	s_add_u32 s41, s41, 0x400
	global_load_lds_dwordx4 v220, s[64:65]
	s_mov_b32 m0, s41
	s_add_u32 s41, s41, 0x400
	global_load_lds_dwordx4 v220, s[68:69]
	s_mov_b32 m0, s41
	s_nop 0
	global_load_lds_dwordx4 v220, vcc
	v_add_u32_e32 v220, 0x80, v2
	ds_read_b128 v[132:135], v217
	ds_read_b128 v[136:139], v217 offset:1024
	ds_read_b128 v[140:143], v217 offset:2048
	ds_read_b128 v[144:147], v217 offset:3072
	ds_read_b128 v[240:243], v216
	ds_read_b128 v[244:247], v216 offset:1024
	ds_read_b128 v[248:251], v216 offset:2048
	ds_read_b128 v[148:151], v216 offset:3072
	v_mov_b32_e32 v4, 0
	v_mov_b32_e32 v5, v4
	v_mov_b32_e32 v6, v4
	v_mov_b32_e32 v7, v4
	v_mov_b32_e32 v8, v4
	v_mov_b32_e32 v9, v4
	v_mov_b32_e32 v10, v4
	v_mov_b32_e32 v11, v4
	v_mov_b32_e32 v12, v4
	v_mov_b32_e32 v13, v4
	v_mov_b32_e32 v14, v4
	v_mov_b32_e32 v15, v4
	v_mov_b32_e32 v16, v4
	v_mov_b32_e32 v17, v4
	v_mov_b32_e32 v18, v4
	v_mov_b32_e32 v19, v4
	v_mov_b32_e32 v20, v4
	v_mov_b32_e32 v21, v4
	v_mov_b32_e32 v22, v4
	v_mov_b32_e32 v23, v4
	v_mov_b32_e32 v24, v4
	v_mov_b32_e32 v25, v4
	v_mov_b32_e32 v26, v4
	v_mov_b32_e32 v27, v4
	v_mov_b32_e32 v28, v4
	v_mov_b32_e32 v29, v4
	v_mov_b32_e32 v30, v4
	v_mov_b32_e32 v31, v4
	v_mov_b32_e32 v32, v4
	v_mov_b32_e32 v33, v4
	v_mov_b32_e32 v34, v4
	v_mov_b32_e32 v35, v4
	v_mov_b32_e32 v36, v4
	v_mov_b32_e32 v37, v4
	v_mov_b32_e32 v38, v4
	v_mov_b32_e32 v39, v4
	v_mov_b32_e32 v40, v4
	v_mov_b32_e32 v41, v4
	v_mov_b32_e32 v42, v4
	v_mov_b32_e32 v43, v4
	v_mov_b32_e32 v44, v4
	v_mov_b32_e32 v45, v4
	v_mov_b32_e32 v46, v4
	v_mov_b32_e32 v47, v4
	v_mov_b32_e32 v48, v4
	v_mov_b32_e32 v49, v4
	v_mov_b32_e32 v50, v4
	v_mov_b32_e32 v51, v4
	v_mov_b32_e32 v52, v4
	v_mov_b32_e32 v53, v4
	v_mov_b32_e32 v54, v4
	v_mov_b32_e32 v55, v4
	v_mov_b32_e32 v56, v4
	v_mov_b32_e32 v57, v4
	v_mov_b32_e32 v58, v4
	v_mov_b32_e32 v59, v4
	v_mov_b32_e32 v60, v4
	v_mov_b32_e32 v61, v4
	v_mov_b32_e32 v62, v4
	v_mov_b32_e32 v63, v4
	v_mov_b32_e32 v64, v4
	v_mov_b32_e32 v65, v4
	v_mov_b32_e32 v66, v4
	v_mov_b32_e32 v67, v4
	v_mov_b32_e32 v68, v4
	v_mov_b32_e32 v69, v4
	v_mov_b32_e32 v70, v4
	v_mov_b32_e32 v71, v4
	v_mov_b32_e32 v72, v4
	v_mov_b32_e32 v73, v4
	v_mov_b32_e32 v74, v4
	v_mov_b32_e32 v75, v4
	v_mov_b32_e32 v76, v4
	v_mov_b32_e32 v77, v4
	v_mov_b32_e32 v78, v4
	v_mov_b32_e32 v79, v4
	v_mov_b32_e32 v80, v4
	v_mov_b32_e32 v81, v4
	v_mov_b32_e32 v82, v4
	v_mov_b32_e32 v83, v4
	v_mov_b32_e32 v84, v4
	v_mov_b32_e32 v85, v4
	v_mov_b32_e32 v86, v4
	v_mov_b32_e32 v87, v4
	v_mov_b32_e32 v88, v4
	v_mov_b32_e32 v89, v4
	v_mov_b32_e32 v90, v4
	v_mov_b32_e32 v91, v4
	v_mov_b32_e32 v92, v4
	v_mov_b32_e32 v93, v4
	v_mov_b32_e32 v94, v4
	v_mov_b32_e32 v95, v4
	v_mov_b32_e32 v96, v4
	v_mov_b32_e32 v97, v4
	v_mov_b32_e32 v98, v4
	v_mov_b32_e32 v99, v4
	v_mov_b32_e32 v100, v4
	v_mov_b32_e32 v101, v4
	v_mov_b32_e32 v102, v4
	v_mov_b32_e32 v103, v4
	v_mov_b32_e32 v104, v4
	v_mov_b32_e32 v105, v4
	v_mov_b32_e32 v106, v4
	v_mov_b32_e32 v107, v4
	v_mov_b32_e32 v108, v4
	v_mov_b32_e32 v109, v4
	v_mov_b32_e32 v110, v4
	v_mov_b32_e32 v111, v4
	v_mov_b32_e32 v112, v4
	v_mov_b32_e32 v113, v4
	v_mov_b32_e32 v114, v4
	v_mov_b32_e32 v115, v4
	v_mov_b32_e32 v116, v4
	v_mov_b32_e32 v117, v4
	v_mov_b32_e32 v118, v4
	v_mov_b32_e32 v119, v4
	v_mov_b32_e32 v120, v4
	v_mov_b32_e32 v121, v4
	v_mov_b32_e32 v122, v4
	v_mov_b32_e32 v123, v4
	v_mov_b32_e32 v124, v4
	v_mov_b32_e32 v125, v4
	v_mov_b32_e32 v126, v4
	v_mov_b32_e32 v127, v4
	v_mov_b32_e32 v128, v4
	v_mov_b32_e32 v129, v4
	v_mov_b32_e32 v130, v4
	v_mov_b32_e32 v131, v4
	s_mov_b32 s40, 0
